# conflict-free p1 exps of the next softmax-finish (11 diff / 8 gqa) moved in front of the barrier to balance VALU vs MFMA in the post-barrier QK segment
# baseline (speedup 1.0000x reference)
; #define SBAR() __builtin_amdgcn_sched_barrier(0)
; #define KWRITE(b, src0, src1) do { if constexpr (ND0 == 4) { *(bf16x8*)(K_lds + (b) * SHM_K + KSWZ(kr, kcb)) = src0; } \
;     else { int kc = sc * 2; *(bf16x8*)(K_lds + (b) * SHM_K + KSWZ(sr, kc)) = src0; *(bf16x8*)(K_lds + (b) * SHM_K + KSWZ(32 + sr, kc)) = src1; } } while (0)
; #define VWRITE_A(b) do { *(bf16x8*)(V_lds + (b) * SHM_V + vst0) = vs0a; *(bf16x8*)(V_lds + (b) * SHM_V + vst1) = vs1a; } while (0)
; #define SWAIT() do { if constexpr (ND0 == 4) asm volatile("s_waitcnt vmcnt(3)" ::: "memory"); else asm volatile("s_waitcnt vmcnt(4)" ::: "memory"); } while (0)
; #define PSM(P0, P1, MN, AL) do { if constexpr (PRE) partialSM_pre(P0, P1, m_reg, AL, 11.541560327111707f); else partialSM(P0, P1, m_reg, MN, AL, C, thr_raw); } while (0)
; #define RESC(a) do { if (__any((a) < 1.f)) { if (hi == 0) al_l[r32] = (a); asm volatile("s_waitcnt lgkmcnt(0)" ::: "memory"); \
;     _Pragma("unroll") for (int d = 0; d < 4; ++d) _Pragma("unroll") for (int r = 0; r < 16; ++r) o[d][r] *= al_l[crow(r, hi)]; } } while (0)
; template <int ND0, int LDQ, int LDK, int LDO> ...
;     ...
;     pv_d0(o, vb0, pa0, pa1, pa2, pa3); KWRITE(0, ks0a, ks1a); PSM(pB0, pB1, mnB, alB);
;     __syncthreads(); SWAIT(); VWRITE_A(0);
;     RESC(alB); __syncthreads();
;     SBAR(); qkt<ND0>(pA0, pA1, Kq0, qr, r32, hi);
.LBB0_148:
	v_exp_f32_e32 v226, v96
	v_exp_f32_e32 v244, v97
	v_exp_f32_e32 v224, v98
	v_exp_f32_e32 v227, v99
	v_exp_f32_e32 v223, v100
	v_exp_f32_e32 v225, v101
	v_exp_f32_e32 v221, v102
	v_exp_f32_e32 v222, v103
	v_exp_f32_e32 v218, v104
	v_exp_f32_e32 v220, v105
	v_exp_f32_e32 v217, v106
	v_exp_f32_e32 v219, v107
	v_exp_f32_e32 v214, v108
	v_exp_f32_e32 v216, v109
	v_exp_f32_e32 v213, v110
	v_exp_f32_e32 v215, v111
	v_exp_f32_e32 v245, v88
	v_exp_f32_e32 v246, v89
	v_exp_f32_e32 v247, v90
	v_exp_f32_e32 v231, v91
	v_exp_f32_e32 v243, v92
	v_exp_f32_e32 v252, v93
	v_exp_f32_e32 v253, v94
	v_exp_f32_e32 v95, v95
	s_waitcnt lgkmcnt(0)
	s_barrier
	ds_read_b128 v[64:67], v199 offset:32768
	ds_read_b128 v[68:71], v199 offset:40960
	s_waitcnt vmcnt(4)
	v_cmp_gt_f32_e32 vcc, 1.0, v210
	s_waitcnt vmcnt(4)
	ds_write_b128 v197, v[158:161]
	ds_write_b128 v198, v[154:157]
	s_cbranch_vccz .LBB0_152
	s_and_saveexec_b64 s[4:5], s[8:9]
	ds_write_b32 v190, v210 offset:128
	s_or_b64 exec, exec, s[4:5]
	s_waitcnt lgkmcnt(0)
	v_add_u32_e32 v76, v185, v112
	ds_read_b128 v[64:67], v76 offset:224
	ds_read_b128 v[68:71], v76 offset:192
	ds_read_b128 v[72:75], v76 offset:160
	ds_read_b128 v[76:79], v76 offset:128
	v_mov_b32_e32 v232, 0x80
	s_waitcnt lgkmcnt(3)
	v_pk_mul_f32 v[12:13], v[12:13], v[64:65]
	s_waitcnt lgkmcnt(2)
	v_pk_mul_f32 v[8:9], v[8:9], v[68:69]
	s_waitcnt lgkmcnt(1)
	v_pk_mul_f32 v[4:5], v[4:5], v[72:73]
	v_pk_mul_f32 v[14:15], v[14:15], v[66:67]
	v_pk_mul_f32 v[10:11], v[10:11], v[70:71]
	v_pk_mul_f32 v[6:7], v[6:7], v[74:75]
	s_waitcnt lgkmcnt(0)
	v_pk_mul_f32 v[2:3], v[2:3], v[78:79]
	v_pk_mul_f32 v[0:1], v[0:1], v[76:77]
	v_pk_mul_f32 v[60:61], v[60:61], v[64:65]
	v_pk_mul_f32 v[56:57], v[56:57], v[68:69]
	v_pk_mul_f32 v[52:53], v[52:53], v[72:73]
	v_pk_mul_f32 v[62:63], v[62:63], v[66:67]
	v_pk_mul_f32 v[58:59], v[58:59], v[70:71]
	v_pk_mul_f32 v[54:55], v[54:55], v[74:75]
	v_pk_mul_f32 v[50:51], v[50:51], v[78:79]
	v_pk_mul_f32 v[48:49], v[48:49], v[76:77]
	v_pk_mul_f32 v[44:45], v[44:45], v[64:65]
	v_pk_mul_f32 v[40:41], v[40:41], v[68:69]
	v_pk_mul_f32 v[36:37], v[36:37], v[72:73]
	v_pk_mul_f32 v[46:47], v[46:47], v[66:67]
	v_pk_mul_f32 v[42:43], v[42:43], v[70:71]
	v_pk_mul_f32 v[38:39], v[38:39], v[74:75]
	v_pk_mul_f32 v[34:35], v[34:35], v[78:79]
	v_pk_mul_f32 v[32:33], v[32:33], v[76:77]
	v_pk_mul_f32 v[28:29], v[28:29], v[64:65]
	v_pk_mul_f32 v[24:25], v[24:25], v[68:69]
	v_pk_mul_f32 v[20:21], v[20:21], v[72:73]
	v_pk_mul_f32 v[30:31], v[30:31], v[66:67]
	v_pk_mul_f32 v[26:27], v[26:27], v[70:71]
	v_pk_mul_f32 v[22:23], v[22:23], v[74:75]
	v_pk_mul_f32 v[18:19], v[18:19], v[78:79]
	v_pk_mul_f32 v[16:17], v[16:17], v[76:77]
	ds_read_b128 v[64:67], v199 offset:32768
	ds_read_b128 v[68:71], v199 offset:40960
	s_waitcnt lgkmcnt(0)
	s_branch .LBB0_153

; #define SBAR() __builtin_amdgcn_sched_barrier(0)
; #define SLOAD_A(k0) do { vs0a = *reinterpret_cast<const bf16x8*>(&Vh[(long)((k0) + sr) * LDK + sc]); vs1a = *reinterpret_cast<const bf16x8*>(&Vh[(long)((k0) + 32 + sr) * LDK + sc]); KLOAD(ks0a, ks1a, k0); } while (0)
; __device__ __forceinline__ void finishSM(f32x16& p0, f32x16& p1, float alpha, float& l_reg, bf16x8& pa0, bf16x8& pa1, bf16x8& pa2, bf16x8& pa3) {
; #pragma unroll
;   for (int r = 0; r < 16; ++r) p1[r] = __builtin_amdgcn_exp2f(p1[r]);
;   float ps = 0;
; #pragma unroll
;   for (int r = 0; r < 16; ++r) ps += p0[r];
; #pragma unroll
;   for (int r = 0; r < 16; ++r) ps += p1[r];
;   { auto rr = __builtin_amdgcn_permlane32_swap(__float_as_uint(ps), __float_as_uint(ps), false, false);
;     ps = __uint_as_float(rr[0]) + __uint_as_float(rr[1]); }
;   l_reg = l_reg * alpha + ps;
;     ...
;   PK4(p0, 0, pa0); PK4(p0, 8, pa1); PK4(p1, 0, pa2); PK4(p1, 8, pa3);
;     ...
; }
; template <int ND0>
; __device__ __forceinline__ void qkt(f32x16& p0, f32x16& p1, const char* Ks, const bf16x8* qr, int r32, int hi) {
;   p0 = f32x16{}; p1 = f32x16{};
; #pragma unroll
;   for (int d0 = 0; d0 < ND0; ++d0) { int cb = (d0 * 16 + hi * 8) * 2;
;     bf16x8 b0 = *reinterpret_cast<const bf16x8*>(Ks + KSWZ(r32, cb));
;     bf16x8 b1 = *reinterpret_cast<const bf16x8*>(Ks + KSWZ(32 + r32, cb));
;     p0 = __builtin_amdgcn_mfma_f32_32x32x16_bf16(b0, qr[d0], p0, 0, 0, 0);
;     p1 = __builtin_amdgcn_mfma_f32_32x32x16_bf16(b1, qr[d0], p1, 0, 0, 0); }
; }
; template <int ND0, int LDQ, int LDK, int LDO> ...
;     ...
;     SBAR(); qkt<ND0>(pA0, pA1, Kq0, qr, r32, hi);
;     finishSM(pB0, pB1, alB, l_reg, pa0, pa1, pa2, pa3); SBAR();
;     if (j + 3 < NT) SLOAD_A((j + 3) * KVBLK); SBAR();
.LBB0_153:
	v_mov_b32_e32 v242, 0x800
	ds_read_b128 v[238:241], v200 offset:32768
	ds_read_b128 v[234:237], v200 offset:40960
	s_waitcnt lgkmcnt(2)
	v_mfma_f32_32x32x16_bf16 v[96:111], v[64:67], v[114:117], 0
	v_mfma_f32_32x32x16_bf16 v[64:79], v[68:71], v[114:117], 0
	s_waitcnt lgkmcnt(0)
	v_mfma_f32_32x32x16_bf16 v[96:111], v[238:241], v[122:125], v[96:111]
	v_mfma_f32_32x32x16_bf16 v[64:79], v[234:237], v[122:125], v[64:79]
	ds_read_b128 v[234:237], v202 offset:32768
	ds_read_b128 v[238:241], v202 offset:40960
	s_waitcnt lgkmcnt(0)
	v_mfma_f32_32x32x16_bf16 v[96:111], v[234:237], v[142:145], v[96:111]
	v_mfma_f32_32x32x16_bf16 v[64:79], v[238:241], v[142:145], v[64:79]
	ds_read_b128 v[234:237], v201 offset:32768
	ds_read_b128 v[238:241], v201 offset:40960
	s_waitcnt lgkmcnt(0)
	v_mfma_f32_32x32x16_bf16 v[96:111], v[234:237], v[138:141], v[96:111]
	v_mfma_f32_32x32x16_bf16 v[64:79], v[238:241], v[138:141], v[64:79]
	ds_read_b128 v[234:237], v203 offset:32768
	ds_read_b128 v[238:241], v203 offset:40960
	s_waitcnt lgkmcnt(0)
	v_mfma_f32_32x32x16_bf16 v[96:111], v[234:237], v[134:137], v[96:111]
	v_mfma_f32_32x32x16_bf16 v[64:79], v[238:241], v[134:137], v[64:79]
	ds_read_b128 v[234:237], v204 offset:32768
	ds_read_b128 v[238:241], v204 offset:40960
	s_waitcnt lgkmcnt(0)
	v_mfma_f32_32x32x16_bf16 v[96:111], v[234:237], v[130:133], v[96:111]
	v_mfma_f32_32x32x16_bf16 v[64:79], v[238:241], v[130:133], v[64:79]
	ds_read_b128 v[234:237], v206 offset:32768
	ds_read_b128 v[238:241], v206 offset:40960
	s_waitcnt lgkmcnt(0)
	v_mfma_f32_32x32x16_bf16 v[96:111], v[234:237], v[126:129], v[96:111]
	v_mfma_f32_32x32x16_bf16 v[64:79], v[238:241], v[126:129], v[64:79]
	ds_read_b128 v[234:237], v205 offset:32768
	ds_read_b128 v[238:241], v205 offset:40960
	s_waitcnt lgkmcnt(0)
	v_mfma_f32_32x32x16_bf16 v[96:111], v[234:237], v[118:121], v[96:111]
	v_exp_f32_e32 v234, v80
	v_add_f32_e32 v80, v244, v226
	v_add_f32_e32 v80, v224, v80
	v_add_f32_e32 v80, v227, v80
	v_add_f32_e32 v80, v223, v80
	v_add_f32_e32 v80, v225, v80
	v_add_f32_e32 v80, v221, v80
	v_add_f32_e32 v80, v222, v80
	v_add_f32_e32 v80, v218, v80
	v_add_f32_e32 v80, v220, v80
	v_add_f32_e32 v80, v217, v80
	v_add_f32_e32 v80, v219, v80
	v_add_f32_e32 v80, v214, v80
	v_exp_f32_e32 v235, v81
	v_add_f32_e32 v80, v216, v80
	v_exp_f32_e32 v236, v82
	v_add_f32_e32 v80, v213, v80
	v_exp_f32_e32 v237, v83
	v_add_f32_e32 v80, v215, v80
	v_mfma_f32_32x32x16_bf16 v[64:79], v[238:241], v[118:121], v[64:79]
	v_exp_f32_e32 v238, v84
	v_add_f32_e32 v80, v234, v80
	v_exp_f32_e32 v239, v85
	v_add_f32_e32 v80, v235, v80
	v_exp_f32_e32 v240, v86
	v_add_f32_e32 v80, v236, v80
	v_exp_f32_e32 v241, v87
	v_add_f32_e32 v80, v237, v80
	v_add_f32_e32 v80, v238, v80
	v_add_f32_e32 v80, v239, v80
	v_add_f32_e32 v80, v240, v80
	v_add_f32_e32 v80, v241, v80
	v_add_f32_e32 v80, v245, v80
	v_add_f32_e32 v80, v246, v80
	v_add_f32_e32 v80, v247, v80
	v_add_f32_e32 v80, v231, v80
	v_add_f32_e32 v80, v243, v80
	v_add_f32_e32 v80, v252, v80
	v_add_f32_e32 v80, v253, v80
	v_add_f32_e32 v211, v95, v80
	v_mov_b32_e32 v212, v211
	v_cvt_pk_bf16_f32 v80, v226, v244
	v_cvt_pk_bf16_f32 v81, v224, v227
	v_cvt_pk_bf16_f32 v82, v223, v225
	v_cvt_pk_bf16_f32 v83, v221, v222
	v_cvt_pk_bf16_f32 v84, v218, v220
	v_cvt_pk_bf16_f32 v85, v217, v219
	v_cvt_pk_bf16_f32 v86, v214, v216
	v_cvt_pk_bf16_f32 v87, v213, v215
	v_cvt_pk_bf16_f32 v88, v234, v235
	v_cvt_pk_bf16_f32 v89, v236, v237
	v_cvt_pk_bf16_f32 v90, v238, v239
	v_cvt_pk_bf16_f32 v91, v240, v241
	v_cvt_pk_bf16_f32 v92, v245, v246
	v_cvt_pk_bf16_f32 v93, v247, v231
	v_cvt_pk_bf16_f32 v94, v243, v252
	v_cvt_pk_bf16_f32 v95, v253, v95
	v_permlane32_swap_b32_e32 v211, v212
	v_permlane32_swap_b32_e32 v80, v82
	v_permlane32_swap_b32_e32 v81, v83
	v_permlane32_swap_b32_e32 v84, v86
	v_permlane32_swap_b32_e32 v85, v87
	v_permlane32_swap_b32_e32 v88, v90
	v_permlane32_swap_b32_e32 v89, v91
	v_permlane32_swap_b32_e32 v92, v94
	v_permlane32_swap_b32_e32 v93, v95
	s_add_i32 s39, s39, 2
	s_cmp_ge_u32 s39, s38
	s_cselect_b64 s[4:5], -1, 0
	s_and_b64 vcc, exec, s[4:5]
	s_cbranch_vccnz .Lgqa_pf_skip
	v_add_co_u32_e32 v146, vcc, 0xfffe8000, v188
	s_nop 1
	v_addc_co_u32_e32 v147, vcc, -1, v189, vcc
	global_load_dwordx4 v[158:161], v[146:147], off
	global_load_dwordx4 v[150:153], v[146:147], off offset:-512
	global_load_dwordx4 v[154:157], v[188:189], off
	global_load_dwordx4 v[146:149], v[188:189], off offset:-512

; #define SBAR() __builtin_amdgcn_sched_barrier(0)
; #define KWRITE(b, src0, src1) do { if constexpr (ND0 == 4) { *(bf16x8*)(K_lds + (b) * SHM_K + KSWZ(kr, kcb)) = src0; } \
;     else { int kc = sc * 2; *(bf16x8*)(K_lds + (b) * SHM_K + KSWZ(sr, kc)) = src0; *(bf16x8*)(K_lds + (b) * SHM_K + KSWZ(32 + sr, kc)) = src1; } } while (0)
; #define SLOAD_A(k0) do { vs0a = *reinterpret_cast<const bf16x8*>(&Vh[(long)((k0) + sr) * LDK + sc]); vs1a = *reinterpret_cast<const bf16x8*>(&Vh[(long)((k0) + 32 + sr) * LDK + sc]); KLOAD(ks0a, ks1a, k0); } while (0)
; #define VWRITE_A(b) do { *(bf16x8*)(V_lds + (b) * SHM_V + vst0) = vs0a; *(bf16x8*)(V_lds + (b) * SHM_V + vst1) = vs1a; } while (0)
; #define SWAIT() do { if constexpr (ND0 == 4) asm volatile("s_waitcnt vmcnt(3)" ::: "memory"); else asm volatile("s_waitcnt vmcnt(4)" ::: "memory"); } while (0)
; #define PSM(P0, P1, MN, AL) do { if constexpr (PRE) partialSM_pre(P0, P1, m_reg, AL, 11.541560327111707f); else partialSM(P0, P1, m_reg, MN, AL, C, thr_raw); } while (0)
; #define RESC(a) do { if (__any((a) < 1.f)) { if (hi == 0) al_l[r32] = (a); asm volatile("s_waitcnt lgkmcnt(0)" ::: "memory"); \
;     _Pragma("unroll") for (int d = 0; d < 4; ++d) _Pragma("unroll") for (int r = 0; r < 16; ++r) o[d][r] *= al_l[crow(r, hi)]; } } while (0)
; template <int ND0, int LDQ, int LDK, int LDO> ...
;     ...
;     pv_d0(o, vb0, pa0, pa1, pa2, pa3); KWRITE(0, ks0a, ks1a); PSM(pB0, pB1, mnB, alB);
;     __syncthreads(); SWAIT(); VWRITE_A(0);
;     RESC(alB); __syncthreads();
;     SBAR(); qkt<ND0>(pA0, pA1, Kq0, qr, r32, hi);
;     finishSM(pB0, pB1, alB, l_reg, pa0, pa1, pa2, pa3); SBAR();
;     if (j + 3 < NT) SLOAD_A((j + 3) * KVBLK); SBAR();
.LBB0_216:
	v_exp_f32_e32 v219, v96
	v_exp_f32_e32 v221, v97
	v_exp_f32_e32 v217, v98
	v_exp_f32_e32 v220, v99
	v_exp_f32_e32 v215, v100
	v_exp_f32_e32 v218, v101
	v_exp_f32_e32 v214, v102
	v_exp_f32_e32 v216, v103
	v_exp_f32_e32 v211, v104
	v_exp_f32_e32 v213, v105
	v_exp_f32_e32 v209, v106
	v_exp_f32_e32 v212, v107
	v_exp_f32_e32 v207, v108
	v_exp_f32_e32 v210, v109
	v_exp_f32_e32 v206, v110
	v_exp_f32_e32 v208, v111
	v_exp_f32_e32 v226, v84
	v_exp_f32_e32 v227, v85
	v_exp_f32_e32 v234, v86
	v_exp_f32_e32 v235, v87
	v_exp_f32_e32 v236, v88
	v_exp_f32_e32 v237, v89
	v_exp_f32_e32 v238, v90
	v_exp_f32_e32 v239, v91
	v_exp_f32_e32 v240, v92
	v_exp_f32_e32 v241, v93
	v_exp_f32_e32 v95, v95
	s_waitcnt lgkmcnt(0)
	s_barrier
	ds_read_b128 v[64:67], v197 offset:32768
	ds_read_b128 v[68:71], v197 offset:40960
	s_waitcnt vmcnt(3)
	v_cmp_gt_f32_e32 vcc, 1.0, v203
	s_waitcnt vmcnt(3)
	ds_write_b128 v193, v[130:133]
	ds_write_b128 v194, v[134:137]
	s_cbranch_vccz .LBB0_220
	s_and_saveexec_b64 s[18:19], s[6:7]
	ds_write_b32 v187, v203 offset:128
	s_or_b64 exec, exec, s[18:19]
	s_waitcnt lgkmcnt(0)
	v_add_u32_e32 v76, v161, v112
	ds_read_b128 v[64:67], v76 offset:224
	ds_read_b128 v[68:71], v76 offset:192
	ds_read_b128 v[72:75], v76 offset:160
	ds_read_b128 v[76:79], v76 offset:128
	s_waitcnt lgkmcnt(3)
	v_pk_mul_f32 v[12:13], v[12:13], v[64:65]
	s_waitcnt lgkmcnt(2)
	v_pk_mul_f32 v[8:9], v[8:9], v[68:69]
	s_waitcnt lgkmcnt(1)
	v_pk_mul_f32 v[4:5], v[4:5], v[72:73]
	v_pk_mul_f32 v[14:15], v[14:15], v[66:67]
	v_pk_mul_f32 v[10:11], v[10:11], v[70:71]
	v_pk_mul_f32 v[6:7], v[6:7], v[74:75]
	s_waitcnt lgkmcnt(0)
	v_pk_mul_f32 v[2:3], v[2:3], v[78:79]
	v_pk_mul_f32 v[0:1], v[0:1], v[76:77]
	v_pk_mul_f32 v[60:61], v[60:61], v[64:65]
	v_pk_mul_f32 v[56:57], v[56:57], v[68:69]
	v_pk_mul_f32 v[52:53], v[52:53], v[72:73]
	v_pk_mul_f32 v[62:63], v[62:63], v[66:67]
	v_pk_mul_f32 v[58:59], v[58:59], v[70:71]
	v_pk_mul_f32 v[54:55], v[54:55], v[74:75]
	v_pk_mul_f32 v[50:51], v[50:51], v[78:79]
	v_pk_mul_f32 v[48:49], v[48:49], v[76:77]
	v_pk_mul_f32 v[44:45], v[44:45], v[64:65]
	v_pk_mul_f32 v[40:41], v[40:41], v[68:69]
	v_pk_mul_f32 v[36:37], v[36:37], v[72:73]
	v_pk_mul_f32 v[46:47], v[46:47], v[66:67]
	v_pk_mul_f32 v[42:43], v[42:43], v[70:71]
	v_pk_mul_f32 v[38:39], v[38:39], v[74:75]
	v_pk_mul_f32 v[34:35], v[34:35], v[78:79]
	v_pk_mul_f32 v[32:33], v[32:33], v[76:77]
	v_pk_mul_f32 v[28:29], v[28:29], v[64:65]
	v_pk_mul_f32 v[24:25], v[24:25], v[68:69]
	v_pk_mul_f32 v[20:21], v[20:21], v[72:73]
	v_pk_mul_f32 v[30:31], v[30:31], v[66:67]
	v_pk_mul_f32 v[26:27], v[26:27], v[70:71]
	v_pk_mul_f32 v[22:23], v[22:23], v[74:75]
	v_pk_mul_f32 v[18:19], v[18:19], v[78:79]
	v_pk_mul_f32 v[16:17], v[16:17], v[76:77]
	ds_read_b128 v[64:67], v197 offset:32768
	ds_read_b128 v[68:71], v197 offset:40960
	s_waitcnt lgkmcnt(0)
.LBB0_220:
	ds_read_b128 v[222:225], v198 offset:32768
	ds_read_b128 v[244:247], v198 offset:40960
	s_waitcnt lgkmcnt(2)
	v_mfma_f32_32x32x16_bf16 v[96:111], v[64:67], v[126:129], 0
	v_mfma_f32_32x32x16_bf16 v[64:79], v[68:71], v[126:129], 0
	s_waitcnt lgkmcnt(0)
	v_mfma_f32_32x32x16_bf16 v[96:111], v[222:225], v[122:125], v[96:111]
	v_mfma_f32_32x32x16_bf16 v[64:79], v[244:247], v[122:125], v[64:79]
	ds_read_b128 v[130:133], v199 offset:32768
	ds_read_b128 v[134:137], v199 offset:40960
	s_waitcnt lgkmcnt(0)
	v_mfma_f32_32x32x16_bf16 v[96:111], v[130:133], v[118:121], v[96:111]
	v_mfma_f32_32x32x16_bf16 v[64:79], v[134:137], v[118:121], v[64:79]
	ds_read_b128 v[138:141], v196 offset:32768
	ds_read_b128 v[244:247], v196 offset:40960
	s_waitcnt lgkmcnt(0)
	v_mfma_f32_32x32x16_bf16 v[96:111], v[138:141], v[114:117], v[96:111]
	v_exp_f32_e32 v222, v80
	v_add_f32_e32 v80, v221, v219
	v_add_f32_e32 v80, v217, v80
	v_add_f32_e32 v80, v220, v80
	v_add_f32_e32 v80, v215, v80
	v_add_f32_e32 v80, v218, v80
	v_add_f32_e32 v80, v214, v80
	v_add_f32_e32 v80, v216, v80
	v_add_f32_e32 v80, v211, v80
	v_add_f32_e32 v80, v213, v80
	v_add_f32_e32 v80, v209, v80
	v_add_f32_e32 v80, v212, v80
	v_add_f32_e32 v80, v207, v80
	v_exp_f32_e32 v223, v81
	v_add_f32_e32 v80, v210, v80
	v_exp_f32_e32 v224, v82
	v_add_f32_e32 v80, v206, v80
	v_exp_f32_e32 v225, v83
	v_add_f32_e32 v80, v208, v80
	v_add_f32_e32 v80, v222, v80
	v_add_f32_e32 v80, v223, v80
	v_add_f32_e32 v80, v224, v80
	v_add_f32_e32 v80, v225, v80
	v_add_f32_e32 v80, v226, v80
	v_add_f32_e32 v80, v227, v80
	v_add_f32_e32 v80, v234, v80
	v_add_f32_e32 v80, v235, v80
	v_add_f32_e32 v80, v236, v80
	v_add_f32_e32 v80, v237, v80
	v_mfma_f32_32x32x16_bf16 v[64:79], v[244:247], v[114:117], v[64:79]
	v_exp_f32_e32 v244, v94
	v_add_f32_e32 v80, v238, v80
	v_add_f32_e32 v80, v239, v80
	v_add_f32_e32 v80, v240, v80
	v_add_f32_e32 v80, v241, v80
	v_add_f32_e32 v80, v244, v80
	v_add_f32_e32 v204, v95, v80
	v_mov_b32_e32 v205, v204
	v_cvt_pk_bf16_f32 v80, v219, v221
	v_cvt_pk_bf16_f32 v81, v217, v220
	v_cvt_pk_bf16_f32 v82, v215, v218
	v_cvt_pk_bf16_f32 v83, v214, v216
	v_cvt_pk_bf16_f32 v84, v211, v213
	v_cvt_pk_bf16_f32 v85, v209, v212
	v_cvt_pk_bf16_f32 v86, v207, v210
	v_cvt_pk_bf16_f32 v87, v206, v208
	v_cvt_pk_bf16_f32 v88, v222, v223
	v_cvt_pk_bf16_f32 v89, v224, v225
	v_cvt_pk_bf16_f32 v90, v226, v227
	v_cvt_pk_bf16_f32 v91, v234, v235
	v_cvt_pk_bf16_f32 v92, v236, v237
	v_cvt_pk_bf16_f32 v93, v238, v239
	v_cvt_pk_bf16_f32 v94, v240, v241
	v_cvt_pk_bf16_f32 v95, v244, v95
	v_permlane32_swap_b32_e32 v204, v205
	v_permlane32_swap_b32_e32 v80, v82
	v_permlane32_swap_b32_e32 v81, v83
	v_permlane32_swap_b32_e32 v84, v86
	v_permlane32_swap_b32_e32 v85, v87
	v_permlane32_swap_b32_e32 v88, v90
	v_permlane32_swap_b32_e32 v89, v91
	v_permlane32_swap_b32_e32 v92, v94
	v_permlane32_swap_b32_e32 v93, v95
	s_cmp_ge_u32 s40, s39
	s_cselect_b64 s[18:19], -1, 0
	s_and_b64 vcc, exec, s[18:19]
	s_cbranch_vccnz .Ldiff_pf_skip
	global_load_dwordx4 v[130:133], v[172:173], off
	v_lshl_add_u64 v[174:175], v[172:173], 0, s[34:35]
	global_load_dwordx4 v[134:137], v[174:175], off
	global_load_dwordx4 v[138:141], v[170:171], off offset:2048
	v_lshl_add_u64 v[172:173], v[172:173], 0, s[46:47]
	v_lshl_add_u64 v[170:171], v[170:171], 0, s[46:47]
